# plus GEMM k-loop stage-1 B fragment read during stage-0 MFMAs
# baseline (speedup 1.0000x reference)
.LBB0_639:
	s_add_i32 s41, s28, 1
	s_cmp_lt_u32 s41, s14
	s_cselect_b32 s29, s41, s28
	s_and_b32 s46, s24, 0x10000
	s_lshl_b32 s34, s29, 6
	s_xor_b32 s50, s46, 0x10000
	s_lshl_b64 s[42:43], s[34:35], 1
	s_add_u32 s48, s2, s42
	s_addc_u32 s49, s3, s43
	v_bitop3_b32 v226, s24, v176, v212 bitop3:0xce
	s_add_u32 s42, s4, s42
	s_waitcnt lgkmcnt(0)
	v_mfma_f32_16x16x32_bf16 v[126:129], v[142:145], v[150:153], v[126:129]
	s_addc_u32 s43, s5, s43
	v_lshl_add_u64 v[186:187], v[154:155], 1, s[48:49]
	v_mov_b32_e32 v161, v1
	v_mfma_f32_16x16x32_bf16 v[122:125], v[138:141], v[150:153], v[122:125]
	v_lshl_add_u64 v[186:187], v[186:187], 0, v[0:1]
	v_lshl_add_u64 v[200:201], v[156:157], 1, s[42:43]
	v_add_u32_e32 v185, s46, v181
	v_mfma_f32_16x16x32_bf16 v[118:121], v[134:137], v[150:153], v[118:121]
	s_add_i32 s28, s28, 2
	s_min_i32 s28, s28, s15
	s_lshl_b32 s28, s28, 6
	v_mfma_f32_16x16x32_bf16 v[114:117], v[130:133], v[150:153], v[114:117]
	v_add_u32_e32 v235, v185, v183
	ds_read_b128 v[244:247], v235 offset:4096
	v_add_u32_e32 v152, v226, v179
	v_lshl_add_u64 v[150:151], v[200:201], 0, v[0:1]
	v_readfirstlane_b32 s29, v152
	v_mfma_f32_16x16x32_bf16 v[110:113], v[142:145], v[146:149], v[110:113]
	v_add_u32_e32 v152, 0x8000, v152
	s_mov_b32 m0, s29
	v_readfirstlane_b32 s29, v152
	v_mfma_f32_16x16x32_bf16 v[106:109], v[138:141], v[146:149], v[106:109]
	global_load_lds_dwordx4 v[186:187], off
	s_mov_b32 m0, s29
	v_mfma_f32_16x16x32_bf16 v[102:105], v[134:137], v[146:149], v[102:105]
	global_load_lds_dwordx4 v[150:151], off
	v_add_u32_e32 v186, v185, v183
	v_mfma_f32_16x16x32_bf16 v[98:101], v[130:133], v[146:149], v[98:101]
	v_lshl_add_u64 v[146:147], v[158:159], 1, s[48:49]
	v_lshl_add_u64 v[148:149], v[164:165], 1, s[42:43]
	v_lshl_add_u64 v[146:147], v[146:147], 0, v[160:161]
	v_lshl_add_u64 v[148:149], v[148:149], 0, v[160:161]
	v_add_u32_e32 v161, v226, v180
	ds_read_b128 v[150:153], v186 offset:6144
	v_readfirstlane_b32 s29, v161
	s_mov_b32 m0, s29
	s_waitcnt lgkmcnt(1)
	v_mfma_f32_16x16x32_bf16 v[94:97], v[142:145], v[244:247], v[94:97]
	global_load_lds_dwordx4 v[146:147], off
	v_add_u32_e32 v146, 0x8000, v161
	v_mfma_f32_16x16x32_bf16 v[90:93], v[138:141], v[244:247], v[90:93]
	v_readfirstlane_b32 s29, v146
	s_mov_b32 m0, s29
	v_bitop3_b32 v146, s24, v182, v212 bitop3:0xce
	global_load_lds_dwordx4 v[148:149], off
	v_mfma_f32_16x16x32_bf16 v[86:89], v[134:137], v[244:247], v[86:89]
	v_add_u32_e32 v233, v146, v183
	v_add3_u32 v187, s46, v177, v176
	v_add3_u32 v231, s46, v178, v176
	v_mfma_f32_16x16x32_bf16 v[82:85], v[130:133], v[244:247], v[82:85]
	ds_read_b128 v[146:149], v186 offset:10240
	ds_read_b128 v[200:203], v186 offset:8192
	v_or_b32_e32 v161, s46, v182
	s_ashr_i32 s29, s28, 31
	s_waitcnt lgkmcnt(2)
	v_mfma_f32_16x16x32_bf16 v[78:81], v[142:145], v[150:153], v[78:81]
	v_add_u32_e32 v230, 0x8000, v187
	v_add_u32_e32 v232, 0x8000, v231
	v_add3_u32 v234, s50, v181, v183
	v_mfma_f32_16x16x32_bf16 v[74:77], v[138:141], v[150:153], v[74:77]
	v_mfma_f32_16x16x32_bf16 v[70:73], v[134:137], v[150:153], v[70:73]
	v_mfma_f32_16x16x32_bf16 v[66:69], v[130:133], v[150:153], v[66:69]
	s_waitcnt lgkmcnt(0)
	ds_read_b128 v[236:239], v186 offset:12288
	v_mfma_f32_16x16x32_bf16 v[46:49], v[142:145], v[146:149], v[46:49]
	v_add_u32_e32 v161, v161, v184
	v_mfma_f32_16x16x32_bf16 v[42:45], v[138:141], v[146:149], v[42:45]
	v_mfma_f32_16x16x32_bf16 v[34:37], v[134:137], v[146:149], v[34:37]
	v_mfma_f32_16x16x32_bf16 v[30:33], v[130:133], v[146:149], v[30:33]
	ds_read_b128 v[240:243], v186 offset:14336
	s_waitcnt lgkmcnt(1)
	v_mfma_f32_16x16x32_bf16 v[38:41], v[142:145], v[236:239], v[38:41]
	v_mfma_f32_16x16x32_bf16 v[26:29], v[138:141], v[236:239], v[26:29]
	v_mfma_f32_16x16x32_bf16 v[22:25], v[134:137], v[236:239], v[22:25]
	v_mfma_f32_16x16x32_bf16 v[18:21], v[130:133], v[236:239], v[18:21]
	v_mfma_f32_16x16x32_bf16 v[62:65], v[142:145], v[200:203], v[62:65]
	v_mfma_f32_16x16x32_bf16 v[58:61], v[138:141], v[200:203], v[58:61]
	v_mfma_f32_16x16x32_bf16 v[54:57], v[134:137], v[200:203], v[54:57]
	v_mfma_f32_16x16x32_bf16 v[50:53], v[130:133], v[200:203], v[50:53]
	s_waitcnt lgkmcnt(0)
	v_mfma_f32_16x16x32_bf16 v[14:17], v[142:145], v[240:243], v[14:17]
	v_mfma_f32_16x16x32_bf16 v[10:13], v[138:141], v[240:243], v[10:13]
	ds_read_b128 v[138:141], v161 offset:32768
	ds_read_b128 v[142:145], v161 offset:34816
	ds_read_b128 v[150:153], v161 offset:36864
	ds_read_b128 v[200:203], v161 offset:38912
	v_add_u32_e32 v161, v185, v184
	v_mfma_f32_16x16x32_bf16 v[6:9], v[134:137], v[240:243], v[6:9]
	ds_read_b128 v[134:137], v161 offset:2048
	ds_read_b128 v[226:229], v161
	v_mfma_f32_16x16x32_bf16 v[2:5], v[130:133], v[240:243], v[2:5]
	ds_read_b128 v[130:133], v161 offset:4096
	s_waitcnt lgkmcnt(0)
	v_mfma_f32_16x16x32_bf16 v[110:113], v[138:141], v[134:137], v[110:113]
	v_mfma_f32_16x16x32_bf16 v[94:97], v[138:141], v[130:133], v[94:97]
	v_mfma_f32_16x16x32_bf16 v[90:93], v[142:145], v[130:133], v[90:93]
	v_mfma_f32_16x16x32_bf16 v[86:89], v[150:153], v[130:133], v[86:89]
	v_mfma_f32_16x16x32_bf16 v[82:85], v[200:203], v[130:133], v[82:85]
	ds_read_b128 v[130:133], v161 offset:6144
	v_mfma_f32_16x16x32_bf16 v[106:109], v[142:145], v[134:137], v[106:109]
	v_mfma_f32_16x16x32_bf16 v[102:105], v[150:153], v[134:137], v[102:105]
	v_mfma_f32_16x16x32_bf16 v[98:101], v[200:203], v[134:137], v[98:101]
	ds_read_b128 v[134:137], v161 offset:10240
	ds_read_b128 v[146:149], v161 offset:8192
	v_mfma_f32_16x16x32_bf16 v[126:129], v[138:141], v[226:229], v[126:129]
	v_mfma_f32_16x16x32_bf16 v[122:125], v[142:145], v[226:229], v[122:125]
	v_mfma_f32_16x16x32_bf16 v[118:121], v[150:153], v[226:229], v[118:121]
	v_mfma_f32_16x16x32_bf16 v[114:117], v[200:203], v[226:229], v[114:117]
	s_waitcnt lgkmcnt(0)
	v_mfma_f32_16x16x32_bf16 v[78:81], v[138:141], v[130:133], v[78:81]
	v_mfma_f32_16x16x32_bf16 v[74:77], v[142:145], v[130:133], v[74:77]
	v_mfma_f32_16x16x32_bf16 v[70:73], v[150:153], v[130:133], v[70:73]
	v_mfma_f32_16x16x32_bf16 v[66:69], v[200:203], v[130:133], v[66:69]
	ds_read_b128 v[226:229], v161 offset:14336
	ds_read_b128 v[130:133], v161 offset:12288
	s_lshl_b64 s[28:29], s[28:29], 1
	v_readfirstlane_b32 s34, v187
	v_mfma_f32_16x16x32_bf16 v[46:49], v[138:141], v[134:137], v[46:49]
	s_mov_b32 m0, s34
	v_readfirstlane_b32 s34, v230
	s_waitcnt vmcnt(0)
	v_mfma_f32_16x16x32_bf16 v[42:45], v[142:145], v[134:137], v[42:45]
	s_waitcnt vmcnt(0) lgkmcnt(0)
	s_barrier
	v_mfma_f32_16x16x32_bf16 v[34:37], v[150:153], v[134:137], v[34:37]
	v_mfma_f32_16x16x32_bf16 v[30:33], v[200:203], v[134:137], v[30:33]
	v_lshl_add_u64 v[134:135], v[166:167], 0, s[28:29]
	v_lshl_add_u64 v[136:137], v[168:169], 0, s[28:29]
	global_load_lds_dwordx4 v[134:135], off
	v_mfma_f32_16x16x32_bf16 v[38:41], v[138:141], v[130:133], v[38:41]
	s_mov_b32 m0, s34
	s_nop 0
	global_load_lds_dwordx4 v[136:137], off
	v_mfma_f32_16x16x32_bf16 v[26:29], v[142:145], v[130:133], v[26:29]
	v_mfma_f32_16x16x32_bf16 v[22:25], v[150:153], v[130:133], v[22:25]
	v_mfma_f32_16x16x32_bf16 v[18:21], v[200:203], v[130:133], v[18:21]
	v_lshl_add_u64 v[130:131], v[170:171], 0, s[28:29]
	v_lshl_add_u64 v[132:133], v[172:173], 0, s[28:29]
	v_readfirstlane_b32 s28, v231
	s_mov_b32 m0, s28
	v_readfirstlane_b32 s28, v232
	global_load_lds_dwordx4 v[130:131], off
	s_mov_b32 m0, s28
	v_mfma_f32_16x16x32_bf16 v[62:65], v[138:141], v[146:149], v[62:65]
	global_load_lds_dwordx4 v[132:133], off
	v_mfma_f32_16x16x32_bf16 v[58:61], v[142:145], v[146:149], v[58:61]
	v_mfma_f32_16x16x32_bf16 v[54:57], v[150:153], v[146:149], v[54:57]
	v_mfma_f32_16x16x32_bf16 v[50:53], v[200:203], v[146:149], v[50:53]
	v_mfma_f32_16x16x32_bf16 v[14:17], v[138:141], v[226:229], v[14:17]
	v_mfma_f32_16x16x32_bf16 v[10:13], v[142:145], v[226:229], v[10:13]
	ds_read_b128 v[142:145], v233 offset:32768
	ds_read_b128 v[138:141], v233 offset:34816
	v_mfma_f32_16x16x32_bf16 v[6:9], v[150:153], v[226:229], v[6:9]
	ds_read_b128 v[134:137], v233 offset:36864
	ds_read_b128 v[130:133], v233 offset:38912
	ds_read_b128 v[146:149], v234 offset:2048
	ds_read_b128 v[150:153], v234
	v_mfma_f32_16x16x32_bf16 v[2:5], v[200:203], v[226:229], v[2:5]
	s_add_i32 s24, s24, 0x10000
	s_cmp_eq_u32 s14, s41
	s_mov_b32 s28, s41
	s_cbranch_scc0 .LBB0_639
